# 9920 layer-1 FFN up-weight conversion tiles moved from the first GEMM phase into the idle tail of the half-GLU GEMM phase (hand-written pipelined converter)
# speedup vs baseline: 1.0064x; 1.0024x over previous
.LBB0_342:
	v_readlane_b32 s6, v255, 9
	s_cmp_gt_i32 s6, 0xf13f
	v_readlane_b32 s7, v255, 10
	s_cbranch_scc1 .LBB0_444
	v_readlane_b32 s14, v255, 9
	s_cmpk_gt_u32 s14, 0x3ff
	v_readlane_b32 s15, v255, 10
	s_cbranch_scc1 .LBB0_345
	s_mov_b64 s[6:7], s[0:1]
	s_load_dwordx2 s[6:7], s[6:7], 0xa0
	s_lshl_b32 s3, s14, 1
	s_and_b32 s3, s3, 0x7c0
	s_lshl_b32 s8, s3, 13
	s_movk_i32 s15, 0x800
	s_waitcnt lgkmcnt(0)
	s_add_u32 s6, s6, s8
	s_addc_u32 s7, s7, 0
	s_lshl_b32 s8, s14, 6
	s_and_b32 s10, s8, 0x7c0
	s_lshl_b32 s8, s10, 2
	s_add_u32 s8, s6, s8
	s_addc_u32 s9, s7, 0
	s_lshl_b32 s6, s10, 12
	s_add_u32 s6, s38, s6
	s_addc_u32 s7, s39, 0
	s_lshl_b32 s3, s3, 1
	s_add_u32 s3, s6, s3
	s_addc_u32 s7, s7, 0
	s_add_u32 s6, s3, 0x2c00000
	s_addc_u32 s7, s7, 0
	s_add_i32 s3, s14, 0xfffffc00
	s_cmpk_gt_u32 s3, 0xfff
	s_cbranch_scc0 .LBB0_346
	s_branch .LBB0_347

.LBB0_357:
	v_and_b32_e32 v195, 48, v0
	v_mul_u32_u24_e32 v2, s15, v195
	v_mov_b32_e32 v197, 0
	v_lshlrev_b32_e32 v196, 2, v2
	v_and_b32_e32 v1, 60, v1
	v_lshl_add_u64 v[2:3], s[8:9], 0, v[196:197]
	v_lshlrev_b32_e32 v196, 2, v1
	s_mov_b32 s13, 0
	v_lshl_add_u64 v[10:11], v[2:3], 0, v[196:197]
	s_lshl_b32 s12, s15, 2
	v_lshl_add_u64 v[12:13], v[10:11], 0, s[12:13]
	v_lshl_add_u64 v[18:19], v[12:13], 0, s[12:13]
	v_lshl_add_u64 v[20:21], v[18:19], 0, s[12:13]
	v_lshl_add_u64 v[26:27], v[20:21], 0, s[12:13]
	v_lshl_add_u64 v[28:29], v[26:27], 0, s[12:13]
	v_lshl_add_u64 v[34:35], v[28:29], 0, s[12:13]
	v_lshl_add_u64 v[36:37], v[34:35], 0, s[12:13]
	v_lshl_add_u64 v[38:39], v[36:37], 0, s[12:13]
	v_lshl_add_u64 v[42:43], v[38:39], 0, s[12:13]
	v_lshl_add_u64 v[46:47], v[42:43], 0, s[12:13]
	v_lshl_add_u64 v[50:51], v[46:47], 0, s[12:13]
	v_lshl_add_u64 v[54:55], v[50:51], 0, s[12:13]
	v_lshl_add_u64 v[58:59], v[54:55], 0, s[12:13]
	v_lshl_add_u64 v[62:63], v[58:59], 0, s[12:13]
	global_load_dwordx4 v[2:5], v[10:11], off nt
	global_load_dwordx4 v[6:9], v[12:13], off nt
	s_nop 0
	global_load_dwordx4 v[10:13], v[18:19], off nt
	global_load_dwordx4 v[14:17], v[20:21], off nt
	s_nop 0
	global_load_dwordx4 v[18:21], v[26:27], off nt
	global_load_dwordx4 v[22:25], v[28:29], off nt
	s_nop 0
	global_load_dwordx4 v[26:29], v[34:35], off nt
	global_load_dwordx4 v[30:33], v[36:37], off nt
	v_readlane_b32 s8, v255, 11
	global_load_dwordx4 v[34:37], v[38:39], off nt
	v_readlane_b32 s10, v255, 9
	global_load_dwordx4 v[38:41], v[42:43], off nt
	v_readlane_b32 s9, v255, 12
	global_load_dwordx4 v[42:45], v[46:47], off nt
	s_mov_b32 s40, s23
	global_load_dwordx4 v[46:49], v[50:51], off nt
	v_readlane_b32 s11, v255, 10
	global_load_dwordx4 v[50:53], v[54:55], off nt
	s_nop 0
	global_load_dwordx4 v[54:57], v[58:59], off nt
	s_nop 0
	global_load_dwordx4 v[58:61], v[62:63], off nt
	v_lshl_add_u64 v[62:63], v[62:63], 0, s[12:13]
	global_load_dwordx4 v[62:65], v[62:63], off nt
	s_add_i32 s12, s8, s10
	s_cmp_lt_i32 s12, 0xf140
	s_cselect_b64 s[14:15], -1, 0
	s_cmp_gt_i32 s12, 0xf13f
	s_mov_b64 s[8:9], s[6:7]
	s_cbranch_scc1 .LBB0_377
	s_mov_b64 s[10:11], 0
	s_cmpk_gt_u32 s12, 0x3ff
	s_mov_b64 s[8:9], 0
	s_cbranch_scc1 .LBB0_366
	s_mov_b64 s[8:9], s[0:1]
	s_load_dwordx2 s[8:9], s[8:9], 0xa0
	s_lshl_b32 s10, s12, 1
	s_and_b32 s13, s10, 0x7c0
	s_lshl_b32 s10, s13, 13
	s_waitcnt lgkmcnt(0)
	s_add_u32 s8, s8, s10
	s_addc_u32 s9, s9, 0
	s_lshl_b32 s10, s12, 6
	s_and_b32 s16, s10, 0x7c0
	s_lshl_b32 s10, s16, 2
	s_add_u32 s10, s8, s10
	s_addc_u32 s11, s9, 0
	s_lshl_b32 s8, s16, 12
	s_add_u32 s8, s38, s8
	s_addc_u32 s9, s39, 0
	s_lshl_b32 s13, s13, 1
	s_add_u32 s8, s8, s13
	s_addc_u32 s9, s9, 0
	s_add_u32 s8, s8, 0x2c00000
	s_addc_u32 s9, s9, 0
	s_movk_i32 s13, 0x800
	s_add_i32 s16, s12, 0xfffffc00
	s_cmpk_gt_u32 s16, 0xfff
	s_cbranch_scc0 .LBB0_367

.LBB0_380:
	s_add_i32 s42, s35, s24
	s_cmp_lt_i32 s42, 0xf140
	s_cselect_b64 s[16:17], -1, 0
	s_cmp_gt_i32 s42, 0xf13f
	s_cbranch_scc1 .LBB0_396
	s_cmpk_gt_u32 s42, 0x3ff
	s_cbranch_scc1 .LBB0_383
	s_mov_b64 s[12:13], s[0:1]
	s_load_dwordx2 s[12:13], s[12:13], 0xa0
	s_lshl_b32 s10, s42, 1
	s_and_b32 s10, s10, 0x7c0
	s_lshl_b32 s18, s10, 13
	s_movk_i32 s46, 0x800
	s_waitcnt lgkmcnt(0)
	s_add_u32 s12, s12, s18
	s_addc_u32 s13, s13, 0
	s_lshl_b32 s18, s42, 6
	s_and_b32 s20, s18, 0x7c0
	s_lshl_b32 s18, s20, 2
	s_add_u32 s18, s12, s18
	s_addc_u32 s19, s13, 0
	s_lshl_b32 s12, s20, 12
	s_add_u32 s12, s25, s12
	s_addc_u32 s13, s26, 0
	s_lshl_b32 s10, s10, 1
	s_add_u32 s12, s12, s10
	s_addc_u32 s13, s13, 0
	s_add_i32 s10, s42, 0xfffffc00
	s_cmpk_gt_u32 s10, 0xfff
	s_cbranch_scc0 .LBB0_384
	s_branch .LBB0_385

.LBB0_396:
	s_waitcnt vmcnt(0)
	v_cvt_pk_bf16_f32 v218, v2, v6
	v_cvt_pk_bf16_f32 v219, v10, v14
	v_cvt_pk_bf16_f32 v220, v18, v22
	v_cvt_pk_bf16_f32 v221, v26, v30
	v_cvt_pk_bf16_f32 v222, v34, v38
	v_cvt_pk_bf16_f32 v223, v42, v46
	v_cvt_pk_bf16_f32 v224, v50, v54
	v_cvt_pk_bf16_f32 v225, v58, v62
	ds_write_b128 v1, v[218:221]
	ds_write_b128 v1, v[222:225] offset:16
	v_cvt_pk_bf16_f32 v218, v3, v7
	v_cvt_pk_bf16_f32 v219, v11, v15
	v_cvt_pk_bf16_f32 v220, v19, v23
	v_cvt_pk_bf16_f32 v221, v27, v31
	v_cvt_pk_bf16_f32 v222, v35, v39
	v_cvt_pk_bf16_f32 v223, v43, v47
	v_cvt_pk_bf16_f32 v224, v51, v55
	v_cvt_pk_bf16_f32 v225, v59, v63
	ds_write2_b64 v1, v[218:219], v[220:221] offset0:17 offset1:18
	ds_write2_b64 v1, v[222:223], v[224:225] offset0:19 offset1:20
	v_cvt_pk_bf16_f32 v218, v4, v8
	v_cvt_pk_bf16_f32 v219, v12, v16
	v_cvt_pk_bf16_f32 v220, v20, v24
	v_cvt_pk_bf16_f32 v221, v28, v32
	v_cvt_pk_bf16_f32 v222, v36, v40
	v_cvt_pk_bf16_f32 v223, v44, v48
	v_cvt_pk_bf16_f32 v224, v52, v56
	v_cvt_pk_bf16_f32 v225, v60, v64
	ds_write_b128 v1, v[218:221] offset:272
	ds_write_b128 v1, v[222:225] offset:288
	v_cvt_pk_bf16_f32 v218, v5, v9
	v_cvt_pk_bf16_f32 v219, v13, v17
	v_cvt_pk_bf16_f32 v220, v21, v25
	v_cvt_pk_bf16_f32 v221, v29, v33
	v_cvt_pk_bf16_f32 v222, v37, v41
	v_cvt_pk_bf16_f32 v223, v45, v49
	v_cvt_pk_bf16_f32 v224, v53, v57
	v_cvt_pk_bf16_f32 v225, v61, v65
	ds_write2_b64 v1, v[218:219], v[220:221] offset0:51 offset1:52
	ds_write2_b64 v1, v[222:223], v[224:225] offset0:53 offset1:54
	s_waitcnt lgkmcnt(0)
	v_lshlrev_b32_e32 v202, 1, v200
	ds_read2_b64 v[218:221], v199 offset1:1
	v_lshl_add_u64 v[226:227], s[6:7], 0, v[202:203]
	v_mad_u64_u32 v[222:223], s[18:19], s23, v198, 0
	v_lshl_add_u64 v[228:229], v[222:223], 1, v[226:227]
	ds_read2_b64 v[222:225], v199 offset0:136 offset1:137
	s_waitcnt lgkmcnt(1)
	global_store_dwordx4 v[228:229], v[218:221], off
	v_add_u32_e32 v201, 0x880, v199
	v_add_u32_e32 v205, 0xcc0, v199
	v_mad_u64_u32 v[218:219], s[18:19], s23, v204, 0
	v_lshl_add_u64 v[218:219], v[218:219], 1, v[226:227]
	s_waitcnt lgkmcnt(0)
	global_store_dwordx4 v[218:219], v[222:225], off
	ds_read2_b64 v[218:221], v201 offset1:1
	v_add_u32_e32 v207, 0x1100, v199
	v_mad_u64_u32 v[222:223], s[18:19], s23, v206, 0
	v_lshl_add_u64 v[228:229], v[222:223], 1, v[226:227]
	ds_read2_b64 v[222:225], v205 offset1:1
	s_waitcnt lgkmcnt(1)
	global_store_dwordx4 v[228:229], v[218:221], off
	v_add_u32_e32 v209, 0x1540, v199
	v_add_u32_e32 v211, 0x1980, v199
	v_mad_u64_u32 v[218:219], s[18:19], s23, v208, 0
	v_lshl_add_u64 v[218:219], v[218:219], 1, v[226:227]
	s_waitcnt lgkmcnt(0)
	global_store_dwordx4 v[218:219], v[222:225], off
	ds_read2_b64 v[218:221], v207 offset1:1
	v_add_u32_e32 v213, 0x1dc0, v199
	v_mad_u64_u32 v[222:223], s[18:19], s23, v210, 0
	v_lshl_add_u64 v[228:229], v[222:223], 1, v[226:227]
	ds_read2_b64 v[222:225], v209 offset1:1
	s_waitcnt lgkmcnt(1)
	global_store_dwordx4 v[228:229], v[218:221], off
	s_andn2_b64 vcc, exec, s[14:15]
	s_nop 0
	v_mad_u64_u32 v[218:219], s[18:19], s23, v212, 0
	v_lshl_add_u64 v[218:219], v[218:219], 1, v[226:227]
	s_waitcnt lgkmcnt(0)
	global_store_dwordx4 v[218:219], v[222:225], off
	ds_read2_b64 v[218:221], v211 offset1:1
	s_nop 0
	v_mad_u64_u32 v[222:223], s[18:19], s23, v214, 0
	v_lshl_add_u64 v[228:229], v[222:223], 1, v[226:227]
	ds_read2_b64 v[222:225], v213 offset1:1
	s_waitcnt lgkmcnt(1)
	global_store_dwordx4 v[228:229], v[218:221], off
	s_nop 1
	v_mad_u64_u32 v[218:219], s[18:19], s23, v216, 0
	v_lshl_add_u64 v[218:219], v[218:219], 1, v[226:227]
	s_waitcnt lgkmcnt(0)
	global_store_dwordx4 v[218:219], v[222:225], off
	s_waitcnt lgkmcnt(0)
	s_mov_b64 s[18:19], 0
	s_cbranch_vccnz .LBB0_378
	s_add_i32 s42, s35, s34
	s_cmp_gt_i32 s42, 0xf13f
	s_cselect_b64 s[18:19], -1, 0
	s_and_b64 vcc, exec, s[18:19]
	s_cbranch_vccnz .LBB0_417
	s_cmpk_gt_u32 s42, 0x3ff
	s_cbranch_scc1 .LBB0_404
	s_mov_b64 s[6:7], s[0:1]
	s_load_dwordx2 s[6:7], s[6:7], 0xa0
	s_lshl_b32 s10, s42, 1
	s_and_b32 s10, s10, 0x7c0
	s_lshl_b32 s14, s10, 13
	s_movk_i32 s46, 0x800
	s_waitcnt lgkmcnt(0)
	s_add_u32 s6, s6, s14
	s_addc_u32 s7, s7, 0
	s_lshl_b32 s14, s42, 6
	s_and_b32 s20, s14, 0x7c0
	s_lshl_b32 s14, s20, 2
	s_add_u32 s14, s6, s14
	s_addc_u32 s15, s7, 0
	s_lshl_b32 s6, s20, 12
	s_add_u32 s6, s25, s6
	s_addc_u32 s7, s26, 0
	s_lshl_b32 s10, s10, 1
	s_add_u32 s6, s6, s10
	s_addc_u32 s7, s7, 0
	s_add_i32 s10, s42, 0xfffffc00
	s_cmpk_gt_u32 s10, 0xfff
	s_cbranch_scc0 .LBB0_405
	s_branch .LBB0_406

.LBB0_417:
	v_cvt_pk_bf16_f32 v218, v66, v70
	v_cvt_pk_bf16_f32 v219, v74, v78
	v_cvt_pk_bf16_f32 v220, v82, v86
	v_cvt_pk_bf16_f32 v221, v90, v94
	v_cvt_pk_bf16_f32 v222, v98, v102
	v_cvt_pk_bf16_f32 v223, v106, v110
	v_cvt_pk_bf16_f32 v224, v114, v118
	v_cvt_pk_bf16_f32 v225, v122, v126
	ds_write_b128 v1, v[218:221]
	ds_write_b128 v1, v[222:225] offset:16
	v_cvt_pk_bf16_f32 v218, v67, v71
	v_cvt_pk_bf16_f32 v219, v75, v79
	v_cvt_pk_bf16_f32 v220, v83, v87
	v_cvt_pk_bf16_f32 v221, v91, v95
	v_cvt_pk_bf16_f32 v222, v99, v103
	v_cvt_pk_bf16_f32 v223, v107, v111
	v_cvt_pk_bf16_f32 v224, v115, v119
	v_cvt_pk_bf16_f32 v225, v123, v127
	ds_write2_b64 v1, v[218:219], v[220:221] offset0:17 offset1:18
	ds_write2_b64 v1, v[222:223], v[224:225] offset0:19 offset1:20
	v_cvt_pk_bf16_f32 v218, v68, v72
	v_cvt_pk_bf16_f32 v219, v76, v80
	v_cvt_pk_bf16_f32 v220, v84, v88
	v_cvt_pk_bf16_f32 v221, v92, v96
	v_cvt_pk_bf16_f32 v222, v100, v104
	v_cvt_pk_bf16_f32 v223, v108, v112
	v_cvt_pk_bf16_f32 v224, v116, v120
	v_cvt_pk_bf16_f32 v225, v124, v128
	ds_write_b128 v1, v[218:221] offset:272
	ds_write_b128 v1, v[222:225] offset:288
	v_cvt_pk_bf16_f32 v218, v69, v73
	v_cvt_pk_bf16_f32 v219, v77, v81
	v_cvt_pk_bf16_f32 v220, v85, v89
	v_cvt_pk_bf16_f32 v221, v93, v97
	v_cvt_pk_bf16_f32 v222, v101, v105
	v_cvt_pk_bf16_f32 v223, v109, v113
	v_cvt_pk_bf16_f32 v224, v117, v121
	v_cvt_pk_bf16_f32 v225, v125, v129
	ds_write2_b64 v1, v[218:219], v[220:221] offset0:51 offset1:52
	ds_write2_b64 v1, v[222:223], v[224:225] offset0:53 offset1:54
	s_waitcnt lgkmcnt(0)
	ds_read2_b64 v[218:221], v199 offset1:1
	v_lshl_add_u64 v[226:227], s[8:9], 0, v[202:203]
	v_mad_u64_u32 v[222:223], s[14:15], s40, v198, 0
	v_lshl_add_u64 v[228:229], v[222:223], 1, v[226:227]
	ds_read2_b64 v[222:225], v199 offset0:136 offset1:137
	s_waitcnt lgkmcnt(1)
	global_store_dwordx4 v[228:229], v[218:221], off
	s_andn2_b64 vcc, exec, s[16:17]
	s_nop 0
	v_mad_u64_u32 v[218:219], s[14:15], s40, v204, 0
	v_lshl_add_u64 v[218:219], v[218:219], 1, v[226:227]
	s_waitcnt lgkmcnt(0)
	global_store_dwordx4 v[218:219], v[222:225], off
	ds_read2_b64 v[218:221], v201 offset1:1
	s_nop 0
	v_mad_u64_u32 v[222:223], s[14:15], s40, v206, 0
	v_lshl_add_u64 v[228:229], v[222:223], 1, v[226:227]
	ds_read2_b64 v[222:225], v205 offset1:1
	s_waitcnt lgkmcnt(1)
	global_store_dwordx4 v[228:229], v[218:221], off
	s_nop 1
	v_mad_u64_u32 v[218:219], s[14:15], s40, v208, 0
	v_lshl_add_u64 v[218:219], v[218:219], 1, v[226:227]
	s_waitcnt lgkmcnt(0)
	global_store_dwordx4 v[218:219], v[222:225], off
	ds_read2_b64 v[218:221], v207 offset1:1
	s_nop 0
	v_mad_u64_u32 v[222:223], s[14:15], s40, v210, 0
	v_lshl_add_u64 v[228:229], v[222:223], 1, v[226:227]
	ds_read2_b64 v[222:225], v209 offset1:1
	s_waitcnt lgkmcnt(1)
	global_store_dwordx4 v[228:229], v[218:221], off
	s_nop 1
	v_mad_u64_u32 v[218:219], s[14:15], s40, v212, 0
	v_lshl_add_u64 v[218:219], v[218:219], 1, v[226:227]
	s_waitcnt lgkmcnt(0)
	global_store_dwordx4 v[218:219], v[222:225], off
	ds_read2_b64 v[218:221], v211 offset1:1
	s_nop 0
	v_mad_u64_u32 v[222:223], s[14:15], s40, v214, 0
	v_lshl_add_u64 v[228:229], v[222:223], 1, v[226:227]
	ds_read2_b64 v[222:225], v213 offset1:1
	s_waitcnt lgkmcnt(1)
	global_store_dwordx4 v[228:229], v[218:221], off
	s_nop 1
	v_mad_u64_u32 v[218:219], s[14:15], s40, v216, 0
	v_lshl_add_u64 v[218:219], v[218:219], 1, v[226:227]
	s_waitcnt lgkmcnt(0)
	global_store_dwordx4 v[218:219], v[222:225], off
	s_waitcnt lgkmcnt(0)
	s_cbranch_vccnz .LBB0_425
	v_readlane_b32 s14, v255, 11
	s_add_i32 s43, s42, s14
	v_readlane_b32 s15, v255, 12
	s_cmp_lt_i32 s43, 0xf140
	s_cselect_b64 s[14:15], -1, 0
	s_cmp_gt_i32 s43, 0xf13f
	s_cbranch_scc1 .LBB0_439
	s_cmpk_gt_u32 s43, 0x3ff
	s_cbranch_scc1 .LBB0_426
	s_mov_b64 s[8:9], s[0:1]
	s_load_dwordx2 s[8:9], s[8:9], 0xa0
	s_lshl_b32 s10, s43, 1
	s_and_b32 s10, s10, 0x7c0
	s_lshl_b32 s16, s10, 13
	s_movk_i32 s47, 0x800
	s_waitcnt lgkmcnt(0)
	s_add_u32 s8, s8, s16
	s_addc_u32 s9, s9, 0
	s_lshl_b32 s16, s43, 6
	s_and_b32 s20, s16, 0x7c0
	s_lshl_b32 s16, s20, 2
	s_add_u32 s16, s8, s16
	s_addc_u32 s17, s9, 0
	s_lshl_b32 s8, s20, 12
	s_add_u32 s8, s25, s8
	s_addc_u32 s9, s26, 0
	s_lshl_b32 s10, s10, 1
	s_add_u32 s8, s8, s10
	s_addc_u32 s9, s9, 0
	s_add_i32 s10, s43, 0xfffffc00
	s_cmpk_gt_u32 s10, 0xfff
	s_cbranch_scc0 .LBB0_427
	s_branch .LBB0_428

.LBB0_445:
	s_and_b64 vcc, exec, s[6:7]
	s_cbranch_vccz .LBB0_712
	v_readlane_b32 s14, v255, 9
	s_cmp_lt_i32 s14, 0xf140
	v_readlane_b32 s15, v255, 10
	s_cbranch_scc0 .LBB0_449
	s_cmpk_gt_u32 s14, 0x3ff
	s_cbranch_scc1 .LBB0_454
	s_mov_b64 s[6:7], s[0:1]
	s_load_dwordx2 s[6:7], s[6:7], 0xa0
	s_lshl_b32 s3, s14, 1
	s_and_b32 s3, s3, 0x7c0
	s_lshl_b32 s8, s3, 13
	s_movk_i32 s15, 0x800
	s_waitcnt lgkmcnt(0)
	s_add_u32 s6, s6, s8
	s_addc_u32 s7, s7, 0
	s_lshl_b32 s8, s14, 6
	s_and_b32 s10, s8, 0x7c0
	s_lshl_b32 s8, s10, 2
	s_add_u32 s8, s6, s8
	s_addc_u32 s9, s7, 0
	s_lshl_b32 s6, s10, 12
	s_add_u32 s6, s38, s6
	s_addc_u32 s7, s39, 0
	s_lshl_b32 s3, s3, 1
	s_add_u32 s3, s6, s3
	s_addc_u32 s7, s7, 0
	s_add_u32 s6, s3, 0x2c00000
	s_addc_u32 s7, s7, 0
	s_add_i32 s3, s14, 0xfffffc00
	s_cmpk_gt_u32 s3, 0xfff
	s_cbranch_scc0 .LBB0_455
	s_branch .LBB0_456

.LBB0_466:
	v_and_b32_e32 v1, 48, v0
	v_mul_u32_u24_e32 v2, s15, v1
	v_lshlrev_b32_e32 v4, 2, v0
	v_mov_b32_e32 v197, 0
	v_lshlrev_b32_e32 v196, 2, v2
	v_and_b32_e32 v130, 60, v4
	v_lshl_add_u64 v[2:3], s[8:9], 0, v[196:197]
	v_lshlrev_b32_e32 v196, 2, v130
	s_mov_b32 s13, 0
	v_lshl_add_u64 v[10:11], v[2:3], 0, v[196:197]
	s_lshl_b32 s12, s15, 2
	v_lshl_add_u64 v[12:13], v[10:11], 0, s[12:13]
	v_lshl_add_u64 v[18:19], v[12:13], 0, s[12:13]
	v_lshl_add_u64 v[20:21], v[18:19], 0, s[12:13]
	v_lshl_add_u64 v[26:27], v[20:21], 0, s[12:13]
	v_lshl_add_u64 v[28:29], v[26:27], 0, s[12:13]
	v_lshl_add_u64 v[34:35], v[28:29], 0, s[12:13]
	v_lshl_add_u64 v[36:37], v[34:35], 0, s[12:13]
	v_lshl_add_u64 v[38:39], v[36:37], 0, s[12:13]
	v_lshl_add_u64 v[42:43], v[38:39], 0, s[12:13]
	v_lshl_add_u64 v[46:47], v[42:43], 0, s[12:13]
	v_lshl_add_u64 v[50:51], v[46:47], 0, s[12:13]
	v_lshl_add_u64 v[54:55], v[50:51], 0, s[12:13]
	v_lshl_add_u64 v[58:59], v[54:55], 0, s[12:13]
	v_lshl_add_u64 v[62:63], v[58:59], 0, s[12:13]
	global_load_dwordx4 v[2:5], v[10:11], off nt
	global_load_dwordx4 v[6:9], v[12:13], off nt
	s_nop 0
	global_load_dwordx4 v[10:13], v[18:19], off nt
	global_load_dwordx4 v[14:17], v[20:21], off nt
	s_nop 0
	global_load_dwordx4 v[18:21], v[26:27], off nt
	global_load_dwordx4 v[22:25], v[28:29], off nt
	s_nop 0
	global_load_dwordx4 v[26:29], v[34:35], off nt
	global_load_dwordx4 v[30:33], v[36:37], off nt
	v_readlane_b32 s8, v255, 11
	global_load_dwordx4 v[34:37], v[38:39], off nt
	v_readlane_b32 s10, v255, 9
	global_load_dwordx4 v[38:41], v[42:43], off nt
	v_readlane_b32 s9, v255, 12
	global_load_dwordx4 v[42:45], v[46:47], off nt
	s_mov_b32 s40, s23
	global_load_dwordx4 v[46:49], v[50:51], off nt
	v_readlane_b32 s11, v255, 10
	global_load_dwordx4 v[50:53], v[54:55], off nt
	s_nop 0
	global_load_dwordx4 v[54:57], v[58:59], off nt
	s_nop 0
	global_load_dwordx4 v[58:61], v[62:63], off nt
	v_lshl_add_u64 v[62:63], v[62:63], 0, s[12:13]
	global_load_dwordx4 v[62:65], v[62:63], off nt
	s_add_i32 s12, s8, s10
	s_cmp_lt_i32 s12, 0xf140
	s_cselect_b64 s[14:15], -1, 0
	s_cmp_gt_i32 s12, 0xf13f
	s_mov_b64 s[8:9], s[6:7]
	s_cbranch_scc1 .LBB0_486
	s_mov_b64 s[10:11], 0
	s_cmpk_gt_u32 s12, 0x3ff
	s_mov_b64 s[8:9], 0
	s_cbranch_scc1 .LBB0_475
	s_mov_b64 s[8:9], s[0:1]
	s_load_dwordx2 s[8:9], s[8:9], 0xa0
	s_lshl_b32 s10, s12, 1
	s_and_b32 s13, s10, 0x7c0
	s_lshl_b32 s10, s13, 13
	s_waitcnt lgkmcnt(0)
	s_add_u32 s8, s8, s10
	s_addc_u32 s9, s9, 0
	s_lshl_b32 s10, s12, 6
	s_and_b32 s16, s10, 0x7c0
	s_lshl_b32 s10, s16, 2
	s_add_u32 s10, s8, s10
	s_addc_u32 s11, s9, 0
	s_lshl_b32 s8, s16, 12
	s_add_u32 s8, s38, s8
	s_addc_u32 s9, s39, 0
	s_lshl_b32 s13, s13, 1
	s_add_u32 s8, s8, s13
	s_addc_u32 s9, s9, 0
	s_add_u32 s8, s8, 0x2c00000
	s_addc_u32 s9, s9, 0
	s_movk_i32 s13, 0x800
	s_add_i32 s16, s12, 0xfffffc00
	s_cmpk_gt_u32 s16, 0xfff
	s_cbranch_scc0 .LBB0_476

.LBB0_505:
	s_waitcnt vmcnt(14)
	v_cvt_pk_bf16_f32 v218, v2, v6
	s_waitcnt vmcnt(12)
	v_cvt_pk_bf16_f32 v219, v10, v14
	s_waitcnt vmcnt(10)
	v_cvt_pk_bf16_f32 v220, v18, v22
	s_waitcnt vmcnt(8)
	v_cvt_pk_bf16_f32 v221, v26, v30
	s_waitcnt vmcnt(6)
	v_cvt_pk_bf16_f32 v222, v34, v38
	s_waitcnt vmcnt(4)
	v_cvt_pk_bf16_f32 v223, v42, v46
	s_waitcnt vmcnt(2)
	v_cvt_pk_bf16_f32 v224, v50, v54
	s_waitcnt vmcnt(0)
	v_cvt_pk_bf16_f32 v225, v58, v62
	ds_write_b128 v195, v[218:221]
	ds_write_b128 v195, v[222:225] offset:16
	v_cvt_pk_bf16_f32 v218, v3, v7
	v_cvt_pk_bf16_f32 v219, v11, v15
	v_cvt_pk_bf16_f32 v220, v19, v23
	v_cvt_pk_bf16_f32 v221, v27, v31
	v_cvt_pk_bf16_f32 v222, v35, v39
	v_cvt_pk_bf16_f32 v223, v43, v47
	v_cvt_pk_bf16_f32 v224, v51, v55
	v_cvt_pk_bf16_f32 v225, v59, v63
	ds_write2_b64 v195, v[218:219], v[220:221] offset0:17 offset1:18
	ds_write2_b64 v195, v[222:223], v[224:225] offset0:19 offset1:20
	v_cvt_pk_bf16_f32 v218, v4, v8
	v_cvt_pk_bf16_f32 v219, v12, v16
	v_cvt_pk_bf16_f32 v220, v20, v24
	v_cvt_pk_bf16_f32 v221, v28, v32
	v_cvt_pk_bf16_f32 v222, v36, v40
	v_cvt_pk_bf16_f32 v223, v44, v48
	v_cvt_pk_bf16_f32 v224, v52, v56
	v_cvt_pk_bf16_f32 v225, v60, v64
	ds_write_b128 v195, v[218:221] offset:272
	ds_write_b128 v195, v[222:225] offset:288
	v_cvt_pk_bf16_f32 v218, v5, v9
	v_cvt_pk_bf16_f32 v219, v13, v17
	v_cvt_pk_bf16_f32 v220, v21, v25
	v_cvt_pk_bf16_f32 v221, v29, v33
	v_cvt_pk_bf16_f32 v222, v37, v41
	v_cvt_pk_bf16_f32 v223, v45, v49
	v_cvt_pk_bf16_f32 v224, v53, v57
	v_cvt_pk_bf16_f32 v225, v61, v65
	ds_write2_b64 v195, v[218:219], v[220:221] offset0:51 offset1:52
	ds_write2_b64 v195, v[222:223], v[224:225] offset0:53 offset1:54
	s_waitcnt lgkmcnt(0)
	v_lshlrev_b32_e32 v202, 1, v200
	ds_read2_b64 v[218:221], v199 offset1:1
	v_lshl_add_u64 v[226:227], s[6:7], 0, v[202:203]
	v_mad_u64_u32 v[222:223], s[18:19], s23, v198, 0
	v_lshl_add_u64 v[228:229], v[222:223], 1, v[226:227]
	ds_read2_b64 v[222:225], v199 offset0:136 offset1:137
	s_waitcnt lgkmcnt(1)
	global_store_dwordx4 v[228:229], v[218:221], off
	v_add_u32_e32 v201, 0x880, v199
	v_add_u32_e32 v205, 0xcc0, v199
	v_mad_u64_u32 v[218:219], s[18:19], s23, v204, 0
	v_lshl_add_u64 v[218:219], v[218:219], 1, v[226:227]
	s_waitcnt lgkmcnt(0)
	global_store_dwordx4 v[218:219], v[222:225], off
	ds_read2_b64 v[218:221], v201 offset1:1
	v_add_u32_e32 v207, 0x1100, v199
	v_mad_u64_u32 v[222:223], s[18:19], s23, v206, 0
	v_lshl_add_u64 v[228:229], v[222:223], 1, v[226:227]
	ds_read2_b64 v[222:225], v205 offset1:1
	s_waitcnt lgkmcnt(1)
	global_store_dwordx4 v[228:229], v[218:221], off
	v_add_u32_e32 v209, 0x1540, v199
	v_add_u32_e32 v211, 0x1980, v199
	v_mad_u64_u32 v[218:219], s[18:19], s23, v208, 0
	v_lshl_add_u64 v[218:219], v[218:219], 1, v[226:227]
	s_waitcnt lgkmcnt(0)
	global_store_dwordx4 v[218:219], v[222:225], off
	ds_read2_b64 v[218:221], v207 offset1:1
	v_add_u32_e32 v213, 0x1dc0, v199
	v_mad_u64_u32 v[222:223], s[18:19], s23, v210, 0
	v_lshl_add_u64 v[228:229], v[222:223], 1, v[226:227]
	ds_read2_b64 v[222:225], v209 offset1:1
	s_waitcnt lgkmcnt(1)
	global_store_dwordx4 v[228:229], v[218:221], off
	s_andn2_b64 vcc, exec, s[14:15]
	s_nop 0
	v_mad_u64_u32 v[218:219], s[18:19], s23, v212, 0
	v_lshl_add_u64 v[218:219], v[218:219], 1, v[226:227]
	s_waitcnt lgkmcnt(0)
	global_store_dwordx4 v[218:219], v[222:225], off
	ds_read2_b64 v[218:221], v211 offset1:1
	s_nop 0
	v_mad_u64_u32 v[222:223], s[18:19], s23, v214, 0
	v_lshl_add_u64 v[228:229], v[222:223], 1, v[226:227]
	ds_read2_b64 v[222:225], v213 offset1:1
	s_waitcnt lgkmcnt(1)
	global_store_dwordx4 v[228:229], v[218:221], off
	s_nop 1
	v_mad_u64_u32 v[218:219], s[18:19], s23, v216, 0
	v_lshl_add_u64 v[218:219], v[218:219], 1, v[226:227]
	s_waitcnt lgkmcnt(0)
	global_store_dwordx4 v[218:219], v[222:225], off
	s_waitcnt lgkmcnt(0)
	s_mov_b64 s[18:19], 0
	s_cbranch_vccnz .LBB0_487
	s_add_i32 s42, s35, s34
	s_cmp_gt_i32 s42, 0xf13f
	s_cselect_b64 s[18:19], -1, 0
	s_and_b64 vcc, exec, s[18:19]
	s_cbranch_vccnz .LBB0_526
	s_cmpk_gt_u32 s42, 0x3ff
	s_cbranch_scc1 .LBB0_513
	s_mov_b64 s[6:7], s[0:1]
	s_load_dwordx2 s[6:7], s[6:7], 0xa0
	s_lshl_b32 s10, s42, 1
	s_and_b32 s10, s10, 0x7c0
	s_lshl_b32 s14, s10, 13
	s_movk_i32 s46, 0x800
	s_waitcnt lgkmcnt(0)
	s_add_u32 s6, s6, s14
	s_addc_u32 s7, s7, 0
	s_lshl_b32 s14, s42, 6
	s_and_b32 s20, s14, 0x7c0
	s_lshl_b32 s14, s20, 2
	s_add_u32 s14, s6, s14
	s_addc_u32 s15, s7, 0
	s_lshl_b32 s6, s20, 12
	s_add_u32 s6, s25, s6
	s_addc_u32 s7, s26, 0
	s_lshl_b32 s10, s10, 1
	s_add_u32 s6, s6, s10
	s_addc_u32 s7, s7, 0
	s_add_i32 s10, s42, 0xfffffc00
	s_cmpk_gt_u32 s10, 0xfff
	s_cbranch_scc0 .LBB0_514
	s_branch .LBB0_515

.LBB0_526:
	v_cvt_pk_bf16_f32 v218, v66, v70
	v_cvt_pk_bf16_f32 v219, v74, v78
	v_cvt_pk_bf16_f32 v220, v82, v86
	v_cvt_pk_bf16_f32 v221, v90, v94
	v_cvt_pk_bf16_f32 v222, v98, v102
	v_cvt_pk_bf16_f32 v223, v106, v110
	v_cvt_pk_bf16_f32 v224, v114, v118
	v_cvt_pk_bf16_f32 v225, v122, v126
	ds_write_b128 v195, v[218:221]
	ds_write_b128 v195, v[222:225] offset:16
	v_cvt_pk_bf16_f32 v218, v67, v71
	v_cvt_pk_bf16_f32 v219, v75, v79
	v_cvt_pk_bf16_f32 v220, v83, v87
	v_cvt_pk_bf16_f32 v221, v91, v95
	v_cvt_pk_bf16_f32 v222, v99, v103
	v_cvt_pk_bf16_f32 v223, v107, v111
	v_cvt_pk_bf16_f32 v224, v115, v119
	v_cvt_pk_bf16_f32 v225, v123, v127
	ds_write2_b64 v195, v[218:219], v[220:221] offset0:17 offset1:18
	ds_write2_b64 v195, v[222:223], v[224:225] offset0:19 offset1:20
	v_cvt_pk_bf16_f32 v218, v68, v72
	v_cvt_pk_bf16_f32 v219, v76, v80
	v_cvt_pk_bf16_f32 v220, v84, v88
	v_cvt_pk_bf16_f32 v221, v92, v96
	v_cvt_pk_bf16_f32 v222, v100, v104
	v_cvt_pk_bf16_f32 v223, v108, v112
	v_cvt_pk_bf16_f32 v224, v116, v120
	v_cvt_pk_bf16_f32 v225, v124, v128
	ds_write_b128 v195, v[218:221] offset:272
	ds_write_b128 v195, v[222:225] offset:288
	v_cvt_pk_bf16_f32 v218, v69, v73
	v_cvt_pk_bf16_f32 v219, v77, v81
	v_cvt_pk_bf16_f32 v220, v85, v89
	v_cvt_pk_bf16_f32 v221, v93, v97
	v_cvt_pk_bf16_f32 v222, v101, v105
	v_cvt_pk_bf16_f32 v223, v109, v113
	v_cvt_pk_bf16_f32 v224, v117, v121
	v_cvt_pk_bf16_f32 v225, v125, v129
	ds_write2_b64 v195, v[218:219], v[220:221] offset0:51 offset1:52
	ds_write2_b64 v195, v[222:223], v[224:225] offset0:53 offset1:54
	s_waitcnt lgkmcnt(0)
	ds_read2_b64 v[218:221], v199 offset1:1
	v_lshl_add_u64 v[226:227], s[8:9], 0, v[202:203]
	v_mad_u64_u32 v[222:223], s[14:15], s40, v198, 0
	v_lshl_add_u64 v[228:229], v[222:223], 1, v[226:227]
	ds_read2_b64 v[222:225], v199 offset0:136 offset1:137
	s_waitcnt lgkmcnt(1)
	global_store_dwordx4 v[228:229], v[218:221], off
	s_andn2_b64 vcc, exec, s[16:17]
	s_nop 0
	v_mad_u64_u32 v[218:219], s[14:15], s40, v204, 0
	v_lshl_add_u64 v[218:219], v[218:219], 1, v[226:227]
	s_waitcnt lgkmcnt(0)
	global_store_dwordx4 v[218:219], v[222:225], off
	ds_read2_b64 v[218:221], v201 offset1:1
	s_nop 0
	v_mad_u64_u32 v[222:223], s[14:15], s40, v206, 0
	v_lshl_add_u64 v[228:229], v[222:223], 1, v[226:227]
	ds_read2_b64 v[222:225], v205 offset1:1
	s_waitcnt lgkmcnt(1)
	global_store_dwordx4 v[228:229], v[218:221], off
	s_nop 1
	v_mad_u64_u32 v[218:219], s[14:15], s40, v208, 0
	v_lshl_add_u64 v[218:219], v[218:219], 1, v[226:227]
	s_waitcnt lgkmcnt(0)
	global_store_dwordx4 v[218:219], v[222:225], off
	ds_read2_b64 v[218:221], v207 offset1:1
	s_nop 0
	v_mad_u64_u32 v[222:223], s[14:15], s40, v210, 0
	v_lshl_add_u64 v[228:229], v[222:223], 1, v[226:227]
	ds_read2_b64 v[222:225], v209 offset1:1
	s_waitcnt lgkmcnt(1)
	global_store_dwordx4 v[228:229], v[218:221], off
	s_nop 1
	v_mad_u64_u32 v[218:219], s[14:15], s40, v212, 0
	v_lshl_add_u64 v[218:219], v[218:219], 1, v[226:227]
	s_waitcnt lgkmcnt(0)
	global_store_dwordx4 v[218:219], v[222:225], off
	ds_read2_b64 v[218:221], v211 offset1:1
	s_nop 0
	v_mad_u64_u32 v[222:223], s[14:15], s40, v214, 0
	v_lshl_add_u64 v[228:229], v[222:223], 1, v[226:227]
	ds_read2_b64 v[222:225], v213 offset1:1
	s_waitcnt lgkmcnt(1)
	global_store_dwordx4 v[228:229], v[218:221], off
	s_nop 1
	v_mad_u64_u32 v[218:219], s[14:15], s40, v216, 0
	v_lshl_add_u64 v[218:219], v[218:219], 1, v[226:227]
	s_waitcnt lgkmcnt(0)
	global_store_dwordx4 v[218:219], v[222:225], off
	s_waitcnt lgkmcnt(0)
	s_cbranch_vccnz .LBB0_534
	v_readlane_b32 s14, v255, 11
	s_add_i32 s43, s42, s14
	v_readlane_b32 s15, v255, 12
	s_cmp_lt_i32 s43, 0xf140
	s_cselect_b64 s[14:15], -1, 0
	s_cmp_gt_i32 s43, 0xf13f
	s_cbranch_scc1 .LBB0_548
	s_cmpk_gt_u32 s43, 0x3ff
	s_cbranch_scc1 .LBB0_535
	s_mov_b64 s[8:9], s[0:1]
	s_load_dwordx2 s[8:9], s[8:9], 0xa0
	s_lshl_b32 s10, s43, 1
	s_and_b32 s10, s10, 0x7c0
	s_lshl_b32 s16, s10, 13
	s_movk_i32 s47, 0x800
	s_waitcnt lgkmcnt(0)
	s_add_u32 s8, s8, s16
	s_addc_u32 s9, s9, 0
	s_lshl_b32 s16, s43, 6
	s_and_b32 s20, s16, 0x7c0
	s_lshl_b32 s16, s20, 2
	s_add_u32 s16, s8, s16
	s_addc_u32 s17, s9, 0
	s_lshl_b32 s8, s20, 12
	s_add_u32 s8, s25, s8
	s_addc_u32 s9, s26, 0
	s_lshl_b32 s10, s10, 1
	s_add_u32 s8, s8, s10
	s_addc_u32 s9, s9, 0
	s_add_i32 s10, s43, 0xfffffc00
	s_cmpk_gt_u32 s10, 0xfff
	s_cbranch_scc0 .LBB0_536
	s_branch .LBB0_537

.Ldc_go:
	s_add_i32 s6, s6, 0x440
	s_cmp_gt_u32 s6, 0x2aff
	s_cbranch_scc1 .Ldc_done
	s_load_dwordx2 s[20:21], s[0:1], 0x100
	v_mbcnt_lo_u32_b32 v1, -1, 0
	v_mbcnt_hi_u32_b32 v1, -1, v1
	v_lshrrev_b32_e32 v2, 4, v1
	v_and_b32_e32 v3, 15, v1
	v_mul_u32_u24_e32 v200, 0xac000, v2
	v_lshl_add_u32 v200, v3, 4, v200
	s_lshl_b32 s8, s3, 14
	v_mul_u32_u24_e32 v201, 0x220, v3
	v_lshl_add_u32 v201, v2, 5, v201
	v_add_u32_e32 v201, s8, v201
	v_lshrrev_b32_e32 v2, 3, v1
	v_and_b32_e32 v3, 7, v1
	v_mul_u32_u24_e32 v202, 0x88, v2
	v_lshl_add_u32 v202, v3, 4, v202
	v_add_u32_e32 v202, s8, v202
	v_lshlrev_b32_e32 v203, 13, v2
	v_lshl_add_u32 v203, v3, 4, v203
	s_add_u32 s22, s38, 0x21600000
	s_addc_u32 s23, s39, 0
	s_waitcnt lgkmcnt(0)
	s_add_u32 s20, s20, 0xac00000
	s_addc_u32 s21, s21, 0
	s_mul_hi_u32 s8, s6, 0x5f418
	s_mul_i32 s8, s8, 0x2b00
	s_sub_i32 s25, s6, s8
	s_cmpk_gt_u32 s25, 0x2aff
	s_cselect_b32 s8, 0x2b00, 0
	s_sub_i32 s25, s25, s8
	s_mul_hi_u32 s10, s25, 0x17d05f5
	s_mul_i32 s8, s10, 0xac
	s_sub_i32 s11, s25, s8
	s_mul_i32 s8, s10, 0x2b0000
	s_lshl_b32 s9, s11, 8
	s_add_i32 s8, s8, s9
	s_add_u32 s14, s20, s8
	s_addc_u32 s15, s21, 0
	global_load_dwordx4 v[2:5], v200, s[14:15] nt
	s_add_u32 s14, s14, 0xac00
	s_addc_u32 s15, s15, 0
	global_load_dwordx4 v[6:9], v200, s[14:15] nt
	s_add_u32 s14, s14, 0xac00
	s_addc_u32 s15, s15, 0
	global_load_dwordx4 v[10:13], v200, s[14:15] nt
	s_add_u32 s14, s14, 0xac00
	s_addc_u32 s15, s15, 0
	global_load_dwordx4 v[14:17], v200, s[14:15] nt
	s_add_u32 s14, s14, 0xac00
	s_addc_u32 s15, s15, 0
	global_load_dwordx4 v[18:21], v200, s[14:15] nt
	s_add_u32 s14, s14, 0xac00
	s_addc_u32 s15, s15, 0
	global_load_dwordx4 v[22:25], v200, s[14:15] nt
	s_add_u32 s14, s14, 0xac00
	s_addc_u32 s15, s15, 0
	global_load_dwordx4 v[26:29], v200, s[14:15] nt
	s_add_u32 s14, s14, 0xac00
	s_addc_u32 s15, s15, 0
	global_load_dwordx4 v[30:33], v200, s[14:15] nt
	s_add_u32 s14, s14, 0xac00
	s_addc_u32 s15, s15, 0
	global_load_dwordx4 v[34:37], v200, s[14:15] nt
	s_add_u32 s14, s14, 0xac00
	s_addc_u32 s15, s15, 0
	global_load_dwordx4 v[38:41], v200, s[14:15] nt
	s_add_u32 s14, s14, 0xac00
	s_addc_u32 s15, s15, 0
	global_load_dwordx4 v[42:45], v200, s[14:15] nt
	s_add_u32 s14, s14, 0xac00
	s_addc_u32 s15, s15, 0
	global_load_dwordx4 v[46:49], v200, s[14:15] nt
	s_add_u32 s14, s14, 0xac00
	s_addc_u32 s15, s15, 0
	global_load_dwordx4 v[50:53], v200, s[14:15] nt
	s_add_u32 s14, s14, 0xac00
	s_addc_u32 s15, s15, 0
	global_load_dwordx4 v[54:57], v200, s[14:15] nt
	s_add_u32 s14, s14, 0xac00
	s_addc_u32 s15, s15, 0
	global_load_dwordx4 v[58:61], v200, s[14:15] nt
	s_add_u32 s14, s14, 0xac00
	s_addc_u32 s15, s15, 0
	global_load_dwordx4 v[62:65], v200, s[14:15] nt
.Ldc_loop:
	s_add_i32 s24, s6, s7
	s_cmp_gt_u32 s24, 0x2aff
	s_cbranch_scc1 .Ldc_lastA
	s_mul_hi_u32 s8, s24, 0x5f418
	s_mul_i32 s8, s8, 0x2b00
	s_sub_i32 s25, s24, s8
	s_cmpk_gt_u32 s25, 0x2aff
	s_cselect_b32 s8, 0x2b00, 0
	s_sub_i32 s25, s25, s8
	s_mul_hi_u32 s10, s25, 0x17d05f5
	s_mul_i32 s8, s10, 0xac
	s_sub_i32 s11, s25, s8
	s_mul_i32 s8, s10, 0x2b0000
	s_lshl_b32 s9, s11, 8
	s_add_i32 s8, s8, s9
	s_add_u32 s14, s20, s8
	s_addc_u32 s15, s21, 0
	global_load_dwordx4 v[66:69], v200, s[14:15] nt
	s_add_u32 s14, s14, 0xac00
	s_addc_u32 s15, s15, 0
	global_load_dwordx4 v[70:73], v200, s[14:15] nt
	s_add_u32 s14, s14, 0xac00
	s_addc_u32 s15, s15, 0
	global_load_dwordx4 v[74:77], v200, s[14:15] nt
	s_add_u32 s14, s14, 0xac00
	s_addc_u32 s15, s15, 0
	global_load_dwordx4 v[78:81], v200, s[14:15] nt
	s_add_u32 s14, s14, 0xac00
	s_addc_u32 s15, s15, 0
	global_load_dwordx4 v[82:85], v200, s[14:15] nt
	s_add_u32 s14, s14, 0xac00
	s_addc_u32 s15, s15, 0
	global_load_dwordx4 v[86:89], v200, s[14:15] nt
	s_add_u32 s14, s14, 0xac00
	s_addc_u32 s15, s15, 0
	global_load_dwordx4 v[90:93], v200, s[14:15] nt
	s_add_u32 s14, s14, 0xac00
	s_addc_u32 s15, s15, 0
	global_load_dwordx4 v[94:97], v200, s[14:15] nt
	s_add_u32 s14, s14, 0xac00
	s_addc_u32 s15, s15, 0
	global_load_dwordx4 v[98:101], v200, s[14:15] nt
	s_add_u32 s14, s14, 0xac00
	s_addc_u32 s15, s15, 0
	global_load_dwordx4 v[102:105], v200, s[14:15] nt
	s_add_u32 s14, s14, 0xac00
	s_addc_u32 s15, s15, 0
	global_load_dwordx4 v[106:109], v200, s[14:15] nt
	s_add_u32 s14, s14, 0xac00
	s_addc_u32 s15, s15, 0
	global_load_dwordx4 v[110:113], v200, s[14:15] nt
	s_add_u32 s14, s14, 0xac00
	s_addc_u32 s15, s15, 0
	global_load_dwordx4 v[114:117], v200, s[14:15] nt
	s_add_u32 s14, s14, 0xac00
	s_addc_u32 s15, s15, 0
	global_load_dwordx4 v[118:121], v200, s[14:15] nt
	s_add_u32 s14, s14, 0xac00
	s_addc_u32 s15, s15, 0
	global_load_dwordx4 v[122:125], v200, s[14:15] nt
	s_add_u32 s14, s14, 0xac00
	s_addc_u32 s15, s15, 0
	global_load_dwordx4 v[126:129], v200, s[14:15] nt
	s_waitcnt vmcnt(16)
	s_mul_hi_u32 s8, s6, 0x5f418
	s_mul_i32 s8, s8, 0x2b00
	s_sub_i32 s25, s6, s8
	s_cmpk_gt_u32 s25, 0x2aff
	s_cselect_b32 s8, 0x2b00, 0
	s_sub_i32 s25, s25, s8
	s_mul_hi_u32 s10, s25, 0x17d05f5
	s_mul_i32 s8, s10, 0xac
	s_sub_i32 s11, s25, s8
	s_lshr_b32 s8, s11, 1
	s_lshl_b32 s8, s8, 8
	s_and_b32 s9, s11, 1
	s_lshl_b32 s9, s9, 6
	s_add_i32 s8, s8, s9
	s_addk_i32 s8, 0x80
	s_lshl_b32 s8, s8, 13
	s_lshl_b32 s9, s10, 7
	s_add_i32 s8, s8, s9
	s_add_u32 s18, s22, s8
	s_addc_u32 s19, s23, 0
	v_cvt_pk_bf16_f32 v130, v2, v6
	v_cvt_pk_bf16_f32 v131, v10, v14
	v_cvt_pk_bf16_f32 v132, v18, v22
	v_cvt_pk_bf16_f32 v133, v26, v30
	v_cvt_pk_bf16_f32 v134, v34, v38
	v_cvt_pk_bf16_f32 v135, v42, v46
	v_cvt_pk_bf16_f32 v136, v50, v54
	v_cvt_pk_bf16_f32 v137, v58, v62
	v_cvt_pk_bf16_f32 v138, v3, v7
	v_cvt_pk_bf16_f32 v139, v11, v15
	v_cvt_pk_bf16_f32 v140, v19, v23
	v_cvt_pk_bf16_f32 v141, v27, v31
	v_cvt_pk_bf16_f32 v142, v35, v39
	v_cvt_pk_bf16_f32 v143, v43, v47
	v_cvt_pk_bf16_f32 v144, v51, v55
	v_cvt_pk_bf16_f32 v145, v59, v63
	v_cvt_pk_bf16_f32 v146, v4, v8
	v_cvt_pk_bf16_f32 v147, v12, v16
	v_cvt_pk_bf16_f32 v148, v20, v24
	v_cvt_pk_bf16_f32 v149, v28, v32
	v_cvt_pk_bf16_f32 v150, v36, v40
	v_cvt_pk_bf16_f32 v151, v44, v48
	v_cvt_pk_bf16_f32 v152, v52, v56
	v_cvt_pk_bf16_f32 v153, v60, v64
	v_cvt_pk_bf16_f32 v154, v5, v9
	v_cvt_pk_bf16_f32 v155, v13, v17
	v_cvt_pk_bf16_f32 v156, v21, v25
	v_cvt_pk_bf16_f32 v157, v29, v33
	v_cvt_pk_bf16_f32 v158, v37, v41
	v_cvt_pk_bf16_f32 v159, v45, v49
	v_cvt_pk_bf16_f32 v160, v53, v57
	v_cvt_pk_bf16_f32 v161, v61, v65
	ds_write_b64 v201, v[130:131]
	ds_write_b64 v201, v[132:133] offset:8
	ds_write_b64 v201, v[134:135] offset:16
	ds_write_b64 v201, v[136:137] offset:24
	ds_write_b64 v201, v[138:139] offset:136
	ds_write_b64 v201, v[140:141] offset:144
	ds_write_b64 v201, v[142:143] offset:152
	ds_write_b64 v201, v[144:145] offset:160
	ds_write_b64 v201, v[146:147] offset:272
	ds_write_b64 v201, v[148:149] offset:280
	ds_write_b64 v201, v[150:151] offset:288
	ds_write_b64 v201, v[152:153] offset:296
	ds_write_b64 v201, v[154:155] offset:408
	ds_write_b64 v201, v[156:157] offset:416
	ds_write_b64 v201, v[158:159] offset:424
	ds_write_b64 v201, v[160:161] offset:432
	s_waitcnt lgkmcnt(0)
	ds_read_b64 v[162:163], v202
	ds_read_b64 v[164:165], v202 offset:8
	ds_read_b64 v[166:167], v202 offset:1088
	ds_read_b64 v[168:169], v202 offset:1096
	ds_read_b64 v[170:171], v202 offset:2176
	ds_read_b64 v[172:173], v202 offset:2184
	ds_read_b64 v[174:175], v202 offset:3264
	ds_read_b64 v[176:177], v202 offset:3272
	ds_read_b64 v[178:179], v202 offset:4352
	ds_read_b64 v[180:181], v202 offset:4360
	ds_read_b64 v[182:183], v202 offset:5440
	ds_read_b64 v[184:185], v202 offset:5448
	ds_read_b64 v[186:187], v202 offset:6528
	ds_read_b64 v[188:189], v202 offset:6536
	ds_read_b64 v[190:191], v202 offset:7616
	ds_read_b64 v[192:193], v202 offset:7624
	s_waitcnt lgkmcnt(14)
	global_store_dwordx4 v203, v[162:165], s[18:19]
	s_add_u32 s18, s18, 0x10000
	s_addc_u32 s19, s19, 0
	s_waitcnt lgkmcnt(12)
	global_store_dwordx4 v203, v[166:169], s[18:19]
	s_add_u32 s18, s18, 0x10000
	s_addc_u32 s19, s19, 0
	s_waitcnt lgkmcnt(10)
	global_store_dwordx4 v203, v[170:173], s[18:19]
	s_add_u32 s18, s18, 0x10000
	s_addc_u32 s19, s19, 0
	s_waitcnt lgkmcnt(8)
	global_store_dwordx4 v203, v[174:177], s[18:19]
	s_add_u32 s18, s18, 0x10000
	s_addc_u32 s19, s19, 0
	s_waitcnt lgkmcnt(6)
	global_store_dwordx4 v203, v[178:181], s[18:19]
	s_add_u32 s18, s18, 0x10000
	s_addc_u32 s19, s19, 0
	s_waitcnt lgkmcnt(4)
	global_store_dwordx4 v203, v[182:185], s[18:19]
	s_add_u32 s18, s18, 0x10000
	s_addc_u32 s19, s19, 0
	s_waitcnt lgkmcnt(2)
	global_store_dwordx4 v203, v[186:189], s[18:19]
	s_add_u32 s18, s18, 0x10000
	s_addc_u32 s19, s19, 0
	s_waitcnt lgkmcnt(0)
	global_store_dwordx4 v203, v[190:193], s[18:19]
	s_mov_b32 s6, s24
	s_add_i32 s24, s6, s7
	s_cmp_gt_u32 s24, 0x2aff
	s_cbranch_scc1 .Ldc_lastB
	s_mul_hi_u32 s8, s24, 0x5f418
	s_mul_i32 s8, s8, 0x2b00
	s_sub_i32 s25, s24, s8
	s_cmpk_gt_u32 s25, 0x2aff
	s_cselect_b32 s8, 0x2b00, 0
	s_sub_i32 s25, s25, s8
	s_mul_hi_u32 s10, s25, 0x17d05f5
	s_mul_i32 s8, s10, 0xac
	s_sub_i32 s11, s25, s8
	s_mul_i32 s8, s10, 0x2b0000
	s_lshl_b32 s9, s11, 8
	s_add_i32 s8, s8, s9
	s_add_u32 s14, s20, s8
	s_addc_u32 s15, s21, 0
	global_load_dwordx4 v[2:5], v200, s[14:15] nt
	s_add_u32 s14, s14, 0xac00
	s_addc_u32 s15, s15, 0
	global_load_dwordx4 v[6:9], v200, s[14:15] nt
	s_add_u32 s14, s14, 0xac00
	s_addc_u32 s15, s15, 0
	global_load_dwordx4 v[10:13], v200, s[14:15] nt
	s_add_u32 s14, s14, 0xac00
	s_addc_u32 s15, s15, 0
	global_load_dwordx4 v[14:17], v200, s[14:15] nt
	s_add_u32 s14, s14, 0xac00
	s_addc_u32 s15, s15, 0
	global_load_dwordx4 v[18:21], v200, s[14:15] nt
	s_add_u32 s14, s14, 0xac00
	s_addc_u32 s15, s15, 0
	global_load_dwordx4 v[22:25], v200, s[14:15] nt
	s_add_u32 s14, s14, 0xac00
	s_addc_u32 s15, s15, 0
	global_load_dwordx4 v[26:29], v200, s[14:15] nt
	s_add_u32 s14, s14, 0xac00
	s_addc_u32 s15, s15, 0
	global_load_dwordx4 v[30:33], v200, s[14:15] nt
	s_add_u32 s14, s14, 0xac00
	s_addc_u32 s15, s15, 0
	global_load_dwordx4 v[34:37], v200, s[14:15] nt
	s_add_u32 s14, s14, 0xac00
	s_addc_u32 s15, s15, 0
	global_load_dwordx4 v[38:41], v200, s[14:15] nt
	s_add_u32 s14, s14, 0xac00
	s_addc_u32 s15, s15, 0
	global_load_dwordx4 v[42:45], v200, s[14:15] nt
	s_add_u32 s14, s14, 0xac00
	s_addc_u32 s15, s15, 0
	global_load_dwordx4 v[46:49], v200, s[14:15] nt
	s_add_u32 s14, s14, 0xac00
	s_addc_u32 s15, s15, 0
	global_load_dwordx4 v[50:53], v200, s[14:15] nt
	s_add_u32 s14, s14, 0xac00
	s_addc_u32 s15, s15, 0
	global_load_dwordx4 v[54:57], v200, s[14:15] nt
	s_add_u32 s14, s14, 0xac00
	s_addc_u32 s15, s15, 0
	global_load_dwordx4 v[58:61], v200, s[14:15] nt
	s_add_u32 s14, s14, 0xac00
	s_addc_u32 s15, s15, 0
	global_load_dwordx4 v[62:65], v200, s[14:15] nt
	s_waitcnt vmcnt(16)
	s_mul_hi_u32 s8, s6, 0x5f418
	s_mul_i32 s8, s8, 0x2b00
	s_sub_i32 s25, s6, s8
	s_cmpk_gt_u32 s25, 0x2aff
	s_cselect_b32 s8, 0x2b00, 0
	s_sub_i32 s25, s25, s8
	s_mul_hi_u32 s10, s25, 0x17d05f5
	s_mul_i32 s8, s10, 0xac
	s_sub_i32 s11, s25, s8
	s_lshr_b32 s8, s11, 1
	s_lshl_b32 s8, s8, 8
	s_and_b32 s9, s11, 1
	s_lshl_b32 s9, s9, 6
	s_add_i32 s8, s8, s9
	s_addk_i32 s8, 0x80
	s_lshl_b32 s8, s8, 13
	s_lshl_b32 s9, s10, 7
	s_add_i32 s8, s8, s9
	s_add_u32 s18, s22, s8
	s_addc_u32 s19, s23, 0
	v_cvt_pk_bf16_f32 v130, v66, v70
	v_cvt_pk_bf16_f32 v131, v74, v78
	v_cvt_pk_bf16_f32 v132, v82, v86
	v_cvt_pk_bf16_f32 v133, v90, v94
	v_cvt_pk_bf16_f32 v134, v98, v102
	v_cvt_pk_bf16_f32 v135, v106, v110
	v_cvt_pk_bf16_f32 v136, v114, v118
	v_cvt_pk_bf16_f32 v137, v122, v126
	v_cvt_pk_bf16_f32 v138, v67, v71
	v_cvt_pk_bf16_f32 v139, v75, v79
	v_cvt_pk_bf16_f32 v140, v83, v87
	v_cvt_pk_bf16_f32 v141, v91, v95
	v_cvt_pk_bf16_f32 v142, v99, v103
	v_cvt_pk_bf16_f32 v143, v107, v111
	v_cvt_pk_bf16_f32 v144, v115, v119
	v_cvt_pk_bf16_f32 v145, v123, v127
	v_cvt_pk_bf16_f32 v146, v68, v72
	v_cvt_pk_bf16_f32 v147, v76, v80
	v_cvt_pk_bf16_f32 v148, v84, v88
	v_cvt_pk_bf16_f32 v149, v92, v96
	v_cvt_pk_bf16_f32 v150, v100, v104
	v_cvt_pk_bf16_f32 v151, v108, v112
	v_cvt_pk_bf16_f32 v152, v116, v120
	v_cvt_pk_bf16_f32 v153, v124, v128
	v_cvt_pk_bf16_f32 v154, v69, v73
	v_cvt_pk_bf16_f32 v155, v77, v81
	v_cvt_pk_bf16_f32 v156, v85, v89
	v_cvt_pk_bf16_f32 v157, v93, v97
	v_cvt_pk_bf16_f32 v158, v101, v105
	v_cvt_pk_bf16_f32 v159, v109, v113
	v_cvt_pk_bf16_f32 v160, v117, v121
	v_cvt_pk_bf16_f32 v161, v125, v129
	ds_write_b64 v201, v[130:131]
	ds_write_b64 v201, v[132:133] offset:8
	ds_write_b64 v201, v[134:135] offset:16
	ds_write_b64 v201, v[136:137] offset:24
	ds_write_b64 v201, v[138:139] offset:136
	ds_write_b64 v201, v[140:141] offset:144
	ds_write_b64 v201, v[142:143] offset:152
	ds_write_b64 v201, v[144:145] offset:160
	ds_write_b64 v201, v[146:147] offset:272
	ds_write_b64 v201, v[148:149] offset:280
	ds_write_b64 v201, v[150:151] offset:288
	ds_write_b64 v201, v[152:153] offset:296
	ds_write_b64 v201, v[154:155] offset:408
	ds_write_b64 v201, v[156:157] offset:416
	ds_write_b64 v201, v[158:159] offset:424
	ds_write_b64 v201, v[160:161] offset:432
	s_waitcnt lgkmcnt(0)
	ds_read_b64 v[162:163], v202
	ds_read_b64 v[164:165], v202 offset:8
	ds_read_b64 v[166:167], v202 offset:1088
	ds_read_b64 v[168:169], v202 offset:1096
	ds_read_b64 v[170:171], v202 offset:2176
	ds_read_b64 v[172:173], v202 offset:2184
	ds_read_b64 v[174:175], v202 offset:3264
	ds_read_b64 v[176:177], v202 offset:3272
	ds_read_b64 v[178:179], v202 offset:4352
	ds_read_b64 v[180:181], v202 offset:4360
	ds_read_b64 v[182:183], v202 offset:5440
	ds_read_b64 v[184:185], v202 offset:5448
	ds_read_b64 v[186:187], v202 offset:6528
	ds_read_b64 v[188:189], v202 offset:6536
	ds_read_b64 v[190:191], v202 offset:7616
	ds_read_b64 v[192:193], v202 offset:7624
	s_waitcnt lgkmcnt(14)
	global_store_dwordx4 v203, v[162:165], s[18:19]
	s_add_u32 s18, s18, 0x10000
	s_addc_u32 s19, s19, 0
	s_waitcnt lgkmcnt(12)
	global_store_dwordx4 v203, v[166:169], s[18:19]
	s_add_u32 s18, s18, 0x10000
	s_addc_u32 s19, s19, 0
	s_waitcnt lgkmcnt(10)
	global_store_dwordx4 v203, v[170:173], s[18:19]
	s_add_u32 s18, s18, 0x10000
	s_addc_u32 s19, s19, 0
	s_waitcnt lgkmcnt(8)
	global_store_dwordx4 v203, v[174:177], s[18:19]
	s_add_u32 s18, s18, 0x10000
	s_addc_u32 s19, s19, 0
	s_waitcnt lgkmcnt(6)
	global_store_dwordx4 v203, v[178:181], s[18:19]
	s_add_u32 s18, s18, 0x10000
	s_addc_u32 s19, s19, 0
	s_waitcnt lgkmcnt(4)
	global_store_dwordx4 v203, v[182:185], s[18:19]
	s_add_u32 s18, s18, 0x10000
	s_addc_u32 s19, s19, 0
	s_waitcnt lgkmcnt(2)
	global_store_dwordx4 v203, v[186:189], s[18:19]
	s_add_u32 s18, s18, 0x10000
	s_addc_u32 s19, s19, 0
	s_waitcnt lgkmcnt(0)
	global_store_dwordx4 v203, v[190:193], s[18:19]
	s_mov_b32 s6, s24
	s_branch .Ldc_loop
.Ldc_lastA:
	s_waitcnt vmcnt(0)
	s_mul_hi_u32 s8, s6, 0x5f418
	s_mul_i32 s8, s8, 0x2b00
	s_sub_i32 s25, s6, s8
	s_cmpk_gt_u32 s25, 0x2aff
	s_cselect_b32 s8, 0x2b00, 0
	s_sub_i32 s25, s25, s8
	s_mul_hi_u32 s10, s25, 0x17d05f5
	s_mul_i32 s8, s10, 0xac
	s_sub_i32 s11, s25, s8
	s_lshr_b32 s8, s11, 1
	s_lshl_b32 s8, s8, 8
	s_and_b32 s9, s11, 1
	s_lshl_b32 s9, s9, 6
	s_add_i32 s8, s8, s9
	s_addk_i32 s8, 0x80
	s_lshl_b32 s8, s8, 13
	s_lshl_b32 s9, s10, 7
	s_add_i32 s8, s8, s9
	s_add_u32 s18, s22, s8
	s_addc_u32 s19, s23, 0
	v_cvt_pk_bf16_f32 v130, v2, v6
	v_cvt_pk_bf16_f32 v131, v10, v14
	v_cvt_pk_bf16_f32 v132, v18, v22
	v_cvt_pk_bf16_f32 v133, v26, v30
	v_cvt_pk_bf16_f32 v134, v34, v38
	v_cvt_pk_bf16_f32 v135, v42, v46
	v_cvt_pk_bf16_f32 v136, v50, v54
	v_cvt_pk_bf16_f32 v137, v58, v62
	v_cvt_pk_bf16_f32 v138, v3, v7
	v_cvt_pk_bf16_f32 v139, v11, v15
	v_cvt_pk_bf16_f32 v140, v19, v23
	v_cvt_pk_bf16_f32 v141, v27, v31
	v_cvt_pk_bf16_f32 v142, v35, v39
	v_cvt_pk_bf16_f32 v143, v43, v47
	v_cvt_pk_bf16_f32 v144, v51, v55
	v_cvt_pk_bf16_f32 v145, v59, v63
	v_cvt_pk_bf16_f32 v146, v4, v8
	v_cvt_pk_bf16_f32 v147, v12, v16
	v_cvt_pk_bf16_f32 v148, v20, v24
	v_cvt_pk_bf16_f32 v149, v28, v32
	v_cvt_pk_bf16_f32 v150, v36, v40
	v_cvt_pk_bf16_f32 v151, v44, v48
	v_cvt_pk_bf16_f32 v152, v52, v56
	v_cvt_pk_bf16_f32 v153, v60, v64
	v_cvt_pk_bf16_f32 v154, v5, v9
	v_cvt_pk_bf16_f32 v155, v13, v17
	v_cvt_pk_bf16_f32 v156, v21, v25
	v_cvt_pk_bf16_f32 v157, v29, v33
	v_cvt_pk_bf16_f32 v158, v37, v41
	v_cvt_pk_bf16_f32 v159, v45, v49
	v_cvt_pk_bf16_f32 v160, v53, v57
	v_cvt_pk_bf16_f32 v161, v61, v65
	ds_write_b64 v201, v[130:131]
	ds_write_b64 v201, v[132:133] offset:8
	ds_write_b64 v201, v[134:135] offset:16
	ds_write_b64 v201, v[136:137] offset:24
	ds_write_b64 v201, v[138:139] offset:136
	ds_write_b64 v201, v[140:141] offset:144
	ds_write_b64 v201, v[142:143] offset:152
	ds_write_b64 v201, v[144:145] offset:160
	ds_write_b64 v201, v[146:147] offset:272
	ds_write_b64 v201, v[148:149] offset:280
	ds_write_b64 v201, v[150:151] offset:288
	ds_write_b64 v201, v[152:153] offset:296
	ds_write_b64 v201, v[154:155] offset:408
	ds_write_b64 v201, v[156:157] offset:416
	ds_write_b64 v201, v[158:159] offset:424
	ds_write_b64 v201, v[160:161] offset:432
	s_waitcnt lgkmcnt(0)
	ds_read_b64 v[162:163], v202
	ds_read_b64 v[164:165], v202 offset:8
	ds_read_b64 v[166:167], v202 offset:1088
	ds_read_b64 v[168:169], v202 offset:1096
	ds_read_b64 v[170:171], v202 offset:2176
	ds_read_b64 v[172:173], v202 offset:2184
	ds_read_b64 v[174:175], v202 offset:3264
	ds_read_b64 v[176:177], v202 offset:3272
	ds_read_b64 v[178:179], v202 offset:4352
	ds_read_b64 v[180:181], v202 offset:4360
	ds_read_b64 v[182:183], v202 offset:5440
	ds_read_b64 v[184:185], v202 offset:5448
	ds_read_b64 v[186:187], v202 offset:6528
	ds_read_b64 v[188:189], v202 offset:6536
	ds_read_b64 v[190:191], v202 offset:7616
	ds_read_b64 v[192:193], v202 offset:7624
	s_waitcnt lgkmcnt(14)
	global_store_dwordx4 v203, v[162:165], s[18:19]
	s_add_u32 s18, s18, 0x10000
	s_addc_u32 s19, s19, 0
	s_waitcnt lgkmcnt(12)
	global_store_dwordx4 v203, v[166:169], s[18:19]
	s_add_u32 s18, s18, 0x10000
	s_addc_u32 s19, s19, 0
	s_waitcnt lgkmcnt(10)
	global_store_dwordx4 v203, v[170:173], s[18:19]
	s_add_u32 s18, s18, 0x10000
	s_addc_u32 s19, s19, 0
	s_waitcnt lgkmcnt(8)
	global_store_dwordx4 v203, v[174:177], s[18:19]
	s_add_u32 s18, s18, 0x10000
	s_addc_u32 s19, s19, 0
	s_waitcnt lgkmcnt(6)
	global_store_dwordx4 v203, v[178:181], s[18:19]
	s_add_u32 s18, s18, 0x10000
	s_addc_u32 s19, s19, 0
	s_waitcnt lgkmcnt(4)
	global_store_dwordx4 v203, v[182:185], s[18:19]
	s_add_u32 s18, s18, 0x10000
	s_addc_u32 s19, s19, 0
	s_waitcnt lgkmcnt(2)
	global_store_dwordx4 v203, v[186:189], s[18:19]
	s_add_u32 s18, s18, 0x10000
	s_addc_u32 s19, s19, 0
	s_waitcnt lgkmcnt(0)
	global_store_dwordx4 v203, v[190:193], s[18:19]
	s_branch .Ldc_done
.Ldc_lastB:
	s_waitcnt vmcnt(0)
	s_mul_hi_u32 s8, s6, 0x5f418
	s_mul_i32 s8, s8, 0x2b00
	s_sub_i32 s25, s6, s8
	s_cmpk_gt_u32 s25, 0x2aff
	s_cselect_b32 s8, 0x2b00, 0
	s_sub_i32 s25, s25, s8
	s_mul_hi_u32 s10, s25, 0x17d05f5
	s_mul_i32 s8, s10, 0xac
	s_sub_i32 s11, s25, s8
	s_lshr_b32 s8, s11, 1
	s_lshl_b32 s8, s8, 8
	s_and_b32 s9, s11, 1
	s_lshl_b32 s9, s9, 6
	s_add_i32 s8, s8, s9
	s_addk_i32 s8, 0x80
	s_lshl_b32 s8, s8, 13
	s_lshl_b32 s9, s10, 7
	s_add_i32 s8, s8, s9
	s_add_u32 s18, s22, s8
	s_addc_u32 s19, s23, 0
	v_cvt_pk_bf16_f32 v130, v66, v70
	v_cvt_pk_bf16_f32 v131, v74, v78
	v_cvt_pk_bf16_f32 v132, v82, v86
	v_cvt_pk_bf16_f32 v133, v90, v94
	v_cvt_pk_bf16_f32 v134, v98, v102
	v_cvt_pk_bf16_f32 v135, v106, v110
	v_cvt_pk_bf16_f32 v136, v114, v118
	v_cvt_pk_bf16_f32 v137, v122, v126
	v_cvt_pk_bf16_f32 v138, v67, v71
	v_cvt_pk_bf16_f32 v139, v75, v79
	v_cvt_pk_bf16_f32 v140, v83, v87
	v_cvt_pk_bf16_f32 v141, v91, v95
	v_cvt_pk_bf16_f32 v142, v99, v103
	v_cvt_pk_bf16_f32 v143, v107, v111
	v_cvt_pk_bf16_f32 v144, v115, v119
	v_cvt_pk_bf16_f32 v145, v123, v127
	v_cvt_pk_bf16_f32 v146, v68, v72
	v_cvt_pk_bf16_f32 v147, v76, v80
	v_cvt_pk_bf16_f32 v148, v84, v88
	v_cvt_pk_bf16_f32 v149, v92, v96
	v_cvt_pk_bf16_f32 v150, v100, v104
	v_cvt_pk_bf16_f32 v151, v108, v112
	v_cvt_pk_bf16_f32 v152, v116, v120
	v_cvt_pk_bf16_f32 v153, v124, v128
	v_cvt_pk_bf16_f32 v154, v69, v73
	v_cvt_pk_bf16_f32 v155, v77, v81
	v_cvt_pk_bf16_f32 v156, v85, v89
	v_cvt_pk_bf16_f32 v157, v93, v97
	v_cvt_pk_bf16_f32 v158, v101, v105
	v_cvt_pk_bf16_f32 v159, v109, v113
	v_cvt_pk_bf16_f32 v160, v117, v121
	v_cvt_pk_bf16_f32 v161, v125, v129
	ds_write_b64 v201, v[130:131]
	ds_write_b64 v201, v[132:133] offset:8
	ds_write_b64 v201, v[134:135] offset:16
	ds_write_b64 v201, v[136:137] offset:24
	ds_write_b64 v201, v[138:139] offset:136
	ds_write_b64 v201, v[140:141] offset:144
	ds_write_b64 v201, v[142:143] offset:152
	ds_write_b64 v201, v[144:145] offset:160
	ds_write_b64 v201, v[146:147] offset:272
	ds_write_b64 v201, v[148:149] offset:280
	ds_write_b64 v201, v[150:151] offset:288
	ds_write_b64 v201, v[152:153] offset:296
	ds_write_b64 v201, v[154:155] offset:408
	ds_write_b64 v201, v[156:157] offset:416
	ds_write_b64 v201, v[158:159] offset:424
	ds_write_b64 v201, v[160:161] offset:432
	s_waitcnt lgkmcnt(0)
	ds_read_b64 v[162:163], v202
	ds_read_b64 v[164:165], v202 offset:8
	ds_read_b64 v[166:167], v202 offset:1088
	ds_read_b64 v[168:169], v202 offset:1096
	ds_read_b64 v[170:171], v202 offset:2176
	ds_read_b64 v[172:173], v202 offset:2184
	ds_read_b64 v[174:175], v202 offset:3264
	ds_read_b64 v[176:177], v202 offset:3272
	ds_read_b64 v[178:179], v202 offset:4352
	ds_read_b64 v[180:181], v202 offset:4360
	ds_read_b64 v[182:183], v202 offset:5440
	ds_read_b64 v[184:185], v202 offset:5448
	ds_read_b64 v[186:187], v202 offset:6528
	ds_read_b64 v[188:189], v202 offset:6536
	ds_read_b64 v[190:191], v202 offset:7616
	ds_read_b64 v[192:193], v202 offset:7624
	s_waitcnt lgkmcnt(14)
	global_store_dwordx4 v203, v[162:165], s[18:19]
	s_add_u32 s18, s18, 0x10000
	s_addc_u32 s19, s19, 0
	s_waitcnt lgkmcnt(12)
	global_store_dwordx4 v203, v[166:169], s[18:19]
	s_add_u32 s18, s18, 0x10000
	s_addc_u32 s19, s19, 0
	s_waitcnt lgkmcnt(10)
	global_store_dwordx4 v203, v[170:173], s[18:19]
	s_add_u32 s18, s18, 0x10000
	s_addc_u32 s19, s19, 0
	s_waitcnt lgkmcnt(8)
	global_store_dwordx4 v203, v[174:177], s[18:19]
	s_add_u32 s18, s18, 0x10000
	s_addc_u32 s19, s19, 0
	s_waitcnt lgkmcnt(6)
	global_store_dwordx4 v203, v[178:181], s[18:19]
	s_add_u32 s18, s18, 0x10000
	s_addc_u32 s19, s19, 0
	s_waitcnt lgkmcnt(4)
	global_store_dwordx4 v203, v[182:185], s[18:19]
	s_add_u32 s18, s18, 0x10000
	s_addc_u32 s19, s19, 0
	s_waitcnt lgkmcnt(2)
	global_store_dwordx4 v203, v[186:189], s[18:19]
	s_add_u32 s18, s18, 0x10000
	s_addc_u32 s19, s19, 0
	s_waitcnt lgkmcnt(0)
	global_store_dwordx4 v203, v[190:193], s[18:19]
